# residual epilogue de-serialised + MIDK ssq loads batched + attention Q-load vmcnt ladder removed
# baseline (speedup 1.0000x reference)
; #define PG8_GAS __attribute__((address_space(1)))
;     __device__ __forceinline__ void mid(f32x4 (&acc)[2][2][4][2], const Unit& u, int wr, int fr_in) const {
;         int fr = fr_in; asm volatile("" : "+v"(fr));
; #pragma unroll
;         for (int ai = 0; ai < 2; ++ai)
; #pragma unroll
;             for (int m = 0; m < 4; ++m) {
;                 const float s = 1.0f / sqrtf(((const PG8_GAS float*)ssq)[u.pm * BM + ai * HALF + wr * 64 + m * 16 + fr] * (1.0f / 512.0f) + 1e-6f);
; #pragma unroll
;                 for (int bj = 0; bj < 2; ++bj)
; #pragma unroll
;                     for (int n = 0; n < 2; ++n) acc[ai][bj][m][n] = acc[ai][bj][m][n] * s;
;             }
.LBB0_623:
	v_mov_b32_e32 v0, v5
	s_nop 0
	v_add_u32_e32 v0, s37, v0
	v_add_u32_e32 v2, s42, v0
	v_ashrrev_i32_e32 v3, 31, v2
	v_lshl_add_u64 v[2:3], v[2:3], 2, s[58:59]
	global_load_dword v142, v[2:3], off
	v_add_u32_e32 v2, s43, v0
	v_ashrrev_i32_e32 v3, 31, v2
	v_lshl_add_u64 v[2:3], v[2:3], 2, s[58:59]
	global_load_dword v143, v[2:3], off
	v_add_u32_e32 v2, s17, v0
	v_ashrrev_i32_e32 v3, 31, v2
	v_lshl_add_u64 v[2:3], v[2:3], 2, s[58:59]
	global_load_dword v144, v[2:3], off
	v_add_u32_e32 v2, s95, v0
	v_ashrrev_i32_e32 v3, 31, v2
	v_lshl_add_u64 v[2:3], v[2:3], 2, s[58:59]
	global_load_dword v145, v[2:3], off
	v_add_u32_e32 v2, s33, v0
	v_ashrrev_i32_e32 v3, 31, v2
	v_lshl_add_u64 v[2:3], v[2:3], 2, s[58:59]
	global_load_dword v146, v[2:3], off
	v_add_u32_e32 v2, s14, v0
	v_ashrrev_i32_e32 v3, 31, v2
	v_lshl_add_u64 v[2:3], v[2:3], 2, s[58:59]
	global_load_dword v147, v[2:3], off
	v_add_u32_e32 v2, s15, v0
	v_ashrrev_i32_e32 v3, 31, v2
	v_lshl_add_u64 v[2:3], v[2:3], 2, s[58:59]
	global_load_dword v148, v[2:3], off
	v_add_u32_e32 v2, s98, v0
	v_ashrrev_i32_e32 v3, 31, v2
	v_lshl_add_u64 v[2:3], v[2:3], 2, s[58:59]
	global_load_dword v149, v[2:3], off
	s_waitcnt vmcnt(0)
	v_fmamk_f32 v2, v142, 0x3b000000, v220
	v_cmp_gt_f32_e32 vcc, s45, v2
	v_mul_f32_e32 v3, 0x4f800000, v2
	s_nop 0
	v_cndmask_b32_e32 v2, v2, v3, vcc
	v_sqrt_f32_e32 v3, v2
	s_nop 0
	v_add_u32_e32 v138, -1, v3
	v_fma_f32 v139, -v138, v3, v2
	v_cmp_ge_f32_e64 s[4:5], 0, v139
	v_add_u32_e32 v139, 1, v3
	s_nop 0
	v_cndmask_b32_e64 v138, v3, v138, s[4:5]
	v_fma_f32 v3, -v139, v3, v2
	v_cmp_lt_f32_e64 s[4:5], 0, v3
	s_nop 1
	v_cndmask_b32_e64 v3, v138, v139, s[4:5]
	v_mul_f32_e32 v138, 0x37800000, v3
	v_cndmask_b32_e32 v3, v3, v138, vcc
	v_cmp_class_f32_e32 vcc, v2, v221
	s_nop 1
	v_cndmask_b32_e32 v2, v3, v2, vcc
	v_div_scale_f32 v3, s[4:5], v2, v2, 1.0
	v_rcp_f32_e32 v138, v3
	s_nop 0
	v_fma_f32 v139, -v3, v138, 1.0
	v_fmac_f32_e32 v138, v139, v138
	v_div_scale_f32 v139, vcc, 1.0, v2, 1.0
	v_mul_f32_e32 v140, v139, v138
	v_fma_f32 v141, -v3, v140, v139
	v_fmac_f32_e32 v140, v141, v138
	v_fma_f32 v3, -v3, v140, v139
	v_div_fmas_f32 v3, v3, v138, v140
	v_div_fixup_f32 v2, v3, v2, 1.0
	v_pk_mul_f32 v[132:133], v[132:133], v[2:3] op_sel_hi:[1,0]
	v_pk_mul_f32 v[130:131], v[130:131], v[2:3] op_sel_hi:[1,0]
	v_pk_mul_f32 v[128:129], v[128:129], v[2:3] op_sel_hi:[1,0]
	v_pk_mul_f32 v[126:127], v[126:127], v[2:3] op_sel_hi:[1,0]
	v_pk_mul_f32 v[124:125], v[124:125], v[2:3] op_sel_hi:[1,0]
	v_pk_mul_f32 v[122:123], v[122:123], v[2:3] op_sel_hi:[1,0]
	v_pk_mul_f32 v[120:121], v[120:121], v[2:3] op_sel_hi:[1,0]
	v_pk_mul_f32 v[118:119], v[118:119], v[2:3] op_sel_hi:[1,0]
	v_fmamk_f32 v2, v143, 0x3b000000, v220
	v_cmp_gt_f32_e32 vcc, s45, v2
	v_mul_f32_e32 v3, 0x4f800000, v2
	s_nop 0
	v_cndmask_b32_e32 v2, v2, v3, vcc
	v_sqrt_f32_e32 v3, v2
	s_nop 0
	v_add_u32_e32 v138, -1, v3
	v_fma_f32 v139, -v138, v3, v2
	v_cmp_ge_f32_e64 s[4:5], 0, v139
	v_add_u32_e32 v139, 1, v3
	s_nop 0
	v_cndmask_b32_e64 v138, v3, v138, s[4:5]
	v_fma_f32 v3, -v139, v3, v2
	v_cmp_lt_f32_e64 s[4:5], 0, v3
	s_nop 1
	v_cndmask_b32_e64 v3, v138, v139, s[4:5]
	v_mul_f32_e32 v138, 0x37800000, v3
	v_cndmask_b32_e32 v3, v3, v138, vcc
	v_cmp_class_f32_e32 vcc, v2, v221
	s_nop 1
	v_cndmask_b32_e32 v2, v3, v2, vcc
	v_div_scale_f32 v3, s[4:5], v2, v2, 1.0
	v_rcp_f32_e32 v138, v3
	s_nop 0
	v_fma_f32 v139, -v3, v138, 1.0
	v_fmac_f32_e32 v138, v139, v138
	v_div_scale_f32 v139, vcc, 1.0, v2, 1.0
	v_mul_f32_e32 v140, v139, v138
	v_fma_f32 v141, -v3, v140, v139
	v_fmac_f32_e32 v140, v141, v138
	v_fma_f32 v3, -v3, v140, v139
	v_div_fmas_f32 v3, v3, v138, v140
	v_div_fixup_f32 v2, v3, v2, 1.0
	v_pk_mul_f32 v[116:117], v[116:117], v[2:3] op_sel_hi:[1,0]
	v_pk_mul_f32 v[114:115], v[114:115], v[2:3] op_sel_hi:[1,0]
	v_pk_mul_f32 v[112:113], v[112:113], v[2:3] op_sel_hi:[1,0]
	v_pk_mul_f32 v[110:111], v[110:111], v[2:3] op_sel_hi:[1,0]
	v_pk_mul_f32 v[108:109], v[108:109], v[2:3] op_sel_hi:[1,0]
	v_pk_mul_f32 v[106:107], v[106:107], v[2:3] op_sel_hi:[1,0]
	v_pk_mul_f32 v[104:105], v[104:105], v[2:3] op_sel_hi:[1,0]
	v_pk_mul_f32 v[102:103], v[102:103], v[2:3] op_sel_hi:[1,0]
	v_fmamk_f32 v2, v144, 0x3b000000, v220
	v_cmp_gt_f32_e32 vcc, s45, v2
	v_mul_f32_e32 v3, 0x4f800000, v2
	s_nop 0
	v_cndmask_b32_e32 v2, v2, v3, vcc
	v_sqrt_f32_e32 v3, v2
	s_nop 0
	v_add_u32_e32 v138, -1, v3
	v_fma_f32 v139, -v138, v3, v2
	v_cmp_ge_f32_e64 s[4:5], 0, v139
	v_add_u32_e32 v139, 1, v3
	s_nop 0
	v_cndmask_b32_e64 v138, v3, v138, s[4:5]
	v_fma_f32 v3, -v139, v3, v2
	v_cmp_lt_f32_e64 s[4:5], 0, v3
	s_nop 1
	v_cndmask_b32_e64 v3, v138, v139, s[4:5]
	v_mul_f32_e32 v138, 0x37800000, v3
	v_cndmask_b32_e32 v3, v3, v138, vcc
	v_cmp_class_f32_e32 vcc, v2, v221
	s_nop 1
	v_cndmask_b32_e32 v2, v3, v2, vcc
	v_div_scale_f32 v3, s[4:5], v2, v2, 1.0
	v_rcp_f32_e32 v138, v3
	s_nop 0
	v_fma_f32 v139, -v3, v138, 1.0
	v_fmac_f32_e32 v138, v139, v138
	v_div_scale_f32 v139, vcc, 1.0, v2, 1.0
	v_mul_f32_e32 v140, v139, v138
	v_fma_f32 v141, -v3, v140, v139
	v_fmac_f32_e32 v140, v141, v138
	v_fma_f32 v3, -v3, v140, v139
	v_div_fmas_f32 v3, v3, v138, v140
	v_div_fixup_f32 v2, v3, v2, 1.0
	v_pk_mul_f32 v[100:101], v[100:101], v[2:3] op_sel_hi:[1,0]
	v_pk_mul_f32 v[98:99], v[98:99], v[2:3] op_sel_hi:[1,0]
	v_pk_mul_f32 v[96:97], v[96:97], v[2:3] op_sel_hi:[1,0]
	v_pk_mul_f32 v[94:95], v[94:95], v[2:3] op_sel_hi:[1,0]
	v_pk_mul_f32 v[92:93], v[92:93], v[2:3] op_sel_hi:[1,0]
	v_pk_mul_f32 v[90:91], v[90:91], v[2:3] op_sel_hi:[1,0]
	v_pk_mul_f32 v[88:89], v[88:89], v[2:3] op_sel_hi:[1,0]
	v_pk_mul_f32 v[86:87], v[86:87], v[2:3] op_sel_hi:[1,0]
	v_fmamk_f32 v2, v145, 0x3b000000, v220
; #define PG8_GAS __attribute__((address_space(1)))
;     __device__ __forceinline__ void mid(f32x4 (&acc)[2][2][4][2], const Unit& u, int wr, int fr_in) const {
;         int fr = fr_in; asm volatile("" : "+v"(fr));
; #pragma unroll
;         for (int ai = 0; ai < 2; ++ai)
; #pragma unroll
;             for (int m = 0; m < 4; ++m) {
;                 const float s = 1.0f / sqrtf(((const PG8_GAS float*)ssq)[u.pm * BM + ai * HALF + wr * 64 + m * 16 + fr] * (1.0f / 512.0f) + 1e-6f);
; #pragma unroll
;                 for (int bj = 0; bj < 2; ++bj)
; #pragma unroll
;                     for (int n = 0; n < 2; ++n) acc[ai][bj][m][n] = acc[ai][bj][m][n] * s;
;             }
	v_cmp_gt_f32_e32 vcc, s45, v2
	v_mul_f32_e32 v3, 0x4f800000, v2
	s_nop 0
	v_cndmask_b32_e32 v2, v2, v3, vcc
	v_sqrt_f32_e32 v3, v2
	s_nop 0
	v_add_u32_e32 v138, -1, v3
	v_fma_f32 v139, -v138, v3, v2
	v_cmp_ge_f32_e64 s[4:5], 0, v139
	v_add_u32_e32 v139, 1, v3
	s_nop 0
	v_cndmask_b32_e64 v138, v3, v138, s[4:5]
	v_fma_f32 v3, -v139, v3, v2
	v_cmp_lt_f32_e64 s[4:5], 0, v3
	s_nop 1
	v_cndmask_b32_e64 v3, v138, v139, s[4:5]
	v_mul_f32_e32 v138, 0x37800000, v3
	v_cndmask_b32_e32 v3, v3, v138, vcc
	v_cmp_class_f32_e32 vcc, v2, v221
	s_nop 1
	v_cndmask_b32_e32 v2, v3, v2, vcc
	v_div_scale_f32 v3, s[4:5], v2, v2, 1.0
	v_rcp_f32_e32 v138, v3
	s_nop 0
	v_fma_f32 v139, -v3, v138, 1.0
	v_fmac_f32_e32 v138, v139, v138
	v_div_scale_f32 v139, vcc, 1.0, v2, 1.0
	v_mul_f32_e32 v140, v139, v138
	v_fma_f32 v141, -v3, v140, v139
	v_fmac_f32_e32 v140, v141, v138
	v_fma_f32 v3, -v3, v140, v139
	v_div_fmas_f32 v3, v3, v138, v140
	v_div_fixup_f32 v2, v3, v2, 1.0
	v_pk_mul_f32 v[84:85], v[84:85], v[2:3] op_sel_hi:[1,0]
	v_pk_mul_f32 v[82:83], v[82:83], v[2:3] op_sel_hi:[1,0]
	v_pk_mul_f32 v[80:81], v[80:81], v[2:3] op_sel_hi:[1,0]
	v_pk_mul_f32 v[78:79], v[78:79], v[2:3] op_sel_hi:[1,0]
	v_pk_mul_f32 v[76:77], v[76:77], v[2:3] op_sel_hi:[1,0]
	v_pk_mul_f32 v[74:75], v[74:75], v[2:3] op_sel_hi:[1,0]
	v_pk_mul_f32 v[72:73], v[72:73], v[2:3] op_sel_hi:[1,0]
	v_pk_mul_f32 v[70:71], v[70:71], v[2:3] op_sel_hi:[1,0]
	v_fmamk_f32 v2, v146, 0x3b000000, v220
	v_cmp_gt_f32_e32 vcc, s45, v2
	v_mul_f32_e32 v3, 0x4f800000, v2
	s_nop 0
	v_cndmask_b32_e32 v2, v2, v3, vcc
	v_sqrt_f32_e32 v3, v2
	s_nop 0
	v_add_u32_e32 v138, -1, v3
	v_fma_f32 v139, -v138, v3, v2
	v_cmp_ge_f32_e64 s[4:5], 0, v139
	v_add_u32_e32 v139, 1, v3
	s_nop 0
	v_cndmask_b32_e64 v138, v3, v138, s[4:5]
	v_fma_f32 v3, -v139, v3, v2
	v_cmp_lt_f32_e64 s[4:5], 0, v3
	s_nop 1
	v_cndmask_b32_e64 v3, v138, v139, s[4:5]
	v_mul_f32_e32 v138, 0x37800000, v3
	v_cndmask_b32_e32 v3, v3, v138, vcc
	v_cmp_class_f32_e32 vcc, v2, v221
	s_nop 1
	v_cndmask_b32_e32 v2, v3, v2, vcc
	v_div_scale_f32 v3, s[4:5], v2, v2, 1.0
	v_rcp_f32_e32 v138, v3
	s_nop 0
	v_fma_f32 v139, -v3, v138, 1.0
	v_fmac_f32_e32 v138, v139, v138
	v_div_scale_f32 v139, vcc, 1.0, v2, 1.0
	v_mul_f32_e32 v140, v139, v138
	v_fma_f32 v141, -v3, v140, v139
	v_fmac_f32_e32 v140, v141, v138
	v_fma_f32 v3, -v3, v140, v139
	v_div_fmas_f32 v3, v3, v138, v140
	v_div_fixup_f32 v2, v3, v2, 1.0
	v_pk_mul_f32 v[68:69], v[68:69], v[2:3] op_sel_hi:[1,0]
	v_pk_mul_f32 v[66:67], v[66:67], v[2:3] op_sel_hi:[1,0]
	v_pk_mul_f32 v[64:65], v[64:65], v[2:3] op_sel_hi:[1,0]
	v_pk_mul_f32 v[62:63], v[62:63], v[2:3] op_sel_hi:[1,0]
	v_pk_mul_f32 v[60:61], v[60:61], v[2:3] op_sel_hi:[1,0]
	v_pk_mul_f32 v[58:59], v[58:59], v[2:3] op_sel_hi:[1,0]
	v_pk_mul_f32 v[56:57], v[56:57], v[2:3] op_sel_hi:[1,0]
	v_pk_mul_f32 v[54:55], v[54:55], v[2:3] op_sel_hi:[1,0]
	v_fmamk_f32 v2, v147, 0x3b000000, v220
	v_cmp_gt_f32_e32 vcc, s45, v2
	v_mul_f32_e32 v3, 0x4f800000, v2
	s_nop 0
	v_cndmask_b32_e32 v2, v2, v3, vcc
	v_sqrt_f32_e32 v3, v2
	s_nop 0
	v_add_u32_e32 v138, -1, v3
	v_fma_f32 v139, -v138, v3, v2
	v_cmp_ge_f32_e64 s[4:5], 0, v139
	v_add_u32_e32 v139, 1, v3
	s_nop 0
	v_cndmask_b32_e64 v138, v3, v138, s[4:5]
	v_fma_f32 v3, -v139, v3, v2
	v_cmp_lt_f32_e64 s[4:5], 0, v3
	s_nop 1
	v_cndmask_b32_e64 v3, v138, v139, s[4:5]
	v_mul_f32_e32 v138, 0x37800000, v3
	v_cndmask_b32_e32 v3, v3, v138, vcc
	v_cmp_class_f32_e32 vcc, v2, v221
	s_nop 1
	v_cndmask_b32_e32 v2, v3, v2, vcc
	v_div_scale_f32 v3, s[4:5], v2, v2, 1.0
	v_rcp_f32_e32 v138, v3
	s_nop 0
	v_fma_f32 v139, -v3, v138, 1.0
; #define PG8_GAS __attribute__((address_space(1)))
;     __device__ __forceinline__ void mid(f32x4 (&acc)[2][2][4][2], const Unit& u, int wr, int fr_in) const {
;         int fr = fr_in; asm volatile("" : "+v"(fr));
; #pragma unroll
;         for (int ai = 0; ai < 2; ++ai)
; #pragma unroll
;             for (int m = 0; m < 4; ++m) {
;                 const float s = 1.0f / sqrtf(((const PG8_GAS float*)ssq)[u.pm * BM + ai * HALF + wr * 64 + m * 16 + fr] * (1.0f / 512.0f) + 1e-6f);
; #pragma unroll
;                 for (int bj = 0; bj < 2; ++bj)
; #pragma unroll
;                     for (int n = 0; n < 2; ++n) acc[ai][bj][m][n] = acc[ai][bj][m][n] * s;
;             }
	v_fmac_f32_e32 v138, v139, v138
	v_div_scale_f32 v139, vcc, 1.0, v2, 1.0
	v_mul_f32_e32 v140, v139, v138
	v_fma_f32 v141, -v3, v140, v139
	v_fmac_f32_e32 v140, v141, v138
	v_fma_f32 v3, -v3, v140, v139
	v_div_fmas_f32 v3, v3, v138, v140
	v_div_fixup_f32 v2, v3, v2, 1.0
	v_pk_mul_f32 v[52:53], v[52:53], v[2:3] op_sel_hi:[1,0]
	v_pk_mul_f32 v[50:51], v[50:51], v[2:3] op_sel_hi:[1,0]
	v_pk_mul_f32 v[48:49], v[48:49], v[2:3] op_sel_hi:[1,0]
	v_pk_mul_f32 v[46:47], v[46:47], v[2:3] op_sel_hi:[1,0]
	v_pk_mul_f32 v[44:45], v[44:45], v[2:3] op_sel_hi:[1,0]
	v_pk_mul_f32 v[42:43], v[42:43], v[2:3] op_sel_hi:[1,0]
	v_pk_mul_f32 v[40:41], v[40:41], v[2:3] op_sel_hi:[1,0]
	v_pk_mul_f32 v[38:39], v[38:39], v[2:3] op_sel_hi:[1,0]
	v_fmamk_f32 v2, v148, 0x3b000000, v220
	v_cmp_gt_f32_e32 vcc, s45, v2
	v_mul_f32_e32 v3, 0x4f800000, v2
	s_nop 0
	v_cndmask_b32_e32 v2, v2, v3, vcc
	v_sqrt_f32_e32 v3, v2
	s_nop 0
	v_add_u32_e32 v138, -1, v3
	v_fma_f32 v139, -v138, v3, v2
	v_cmp_ge_f32_e64 s[4:5], 0, v139
	v_add_u32_e32 v139, 1, v3
	s_nop 0
	v_cndmask_b32_e64 v138, v3, v138, s[4:5]
	v_fma_f32 v3, -v139, v3, v2
	v_cmp_lt_f32_e64 s[4:5], 0, v3
	s_nop 1
	v_cndmask_b32_e64 v3, v138, v139, s[4:5]
	v_mul_f32_e32 v138, 0x37800000, v3
	v_cndmask_b32_e32 v3, v3, v138, vcc
	v_cmp_class_f32_e32 vcc, v2, v221
	s_nop 1
	v_cndmask_b32_e32 v2, v3, v2, vcc
	v_div_scale_f32 v3, s[4:5], v2, v2, 1.0
	v_rcp_f32_e32 v138, v3
	s_nop 0
	v_fma_f32 v139, -v3, v138, 1.0
	v_fmac_f32_e32 v138, v139, v138
	v_div_scale_f32 v139, vcc, 1.0, v2, 1.0
	v_mul_f32_e32 v140, v139, v138
	v_fma_f32 v141, -v3, v140, v139
	v_fmac_f32_e32 v140, v141, v138
	v_fma_f32 v3, -v3, v140, v139
	v_div_fmas_f32 v3, v3, v138, v140
	v_div_fixup_f32 v2, v3, v2, 1.0
	v_pk_mul_f32 v[36:37], v[36:37], v[2:3] op_sel_hi:[1,0]
	v_pk_mul_f32 v[34:35], v[34:35], v[2:3] op_sel_hi:[1,0]
	v_pk_mul_f32 v[32:33], v[32:33], v[2:3] op_sel_hi:[1,0]
	v_pk_mul_f32 v[30:31], v[30:31], v[2:3] op_sel_hi:[1,0]
	v_pk_mul_f32 v[28:29], v[28:29], v[2:3] op_sel_hi:[1,0]
	v_pk_mul_f32 v[26:27], v[26:27], v[2:3] op_sel_hi:[1,0]
	v_pk_mul_f32 v[24:25], v[24:25], v[2:3] op_sel_hi:[1,0]
	v_pk_mul_f32 v[22:23], v[22:23], v[2:3] op_sel_hi:[1,0]
	v_fmamk_f32 v0, v149, 0x3b000000, v220
	v_cmp_gt_f32_e32 vcc, s45, v0
	v_mul_f32_e32 v2, 0x4f800000, v0
	s_nop 0
	v_cndmask_b32_e32 v0, v0, v2, vcc
	v_sqrt_f32_e32 v2, v0
	s_nop 0
	v_add_u32_e32 v3, -1, v2
	v_fma_f32 v138, -v3, v2, v0
	v_cmp_ge_f32_e64 s[4:5], 0, v138
	v_add_u32_e32 v138, 1, v2
	s_nop 0
	v_cndmask_b32_e64 v3, v2, v3, s[4:5]
	v_fma_f32 v2, -v138, v2, v0
	v_cmp_lt_f32_e64 s[4:5], 0, v2
	s_nop 1
	v_cndmask_b32_e64 v2, v3, v138, s[4:5]
	v_mul_f32_e32 v3, 0x37800000, v2
	v_cndmask_b32_e32 v2, v2, v3, vcc
	v_cmp_class_f32_e32 vcc, v0, v221
	s_nop 1
	v_cndmask_b32_e32 v0, v2, v0, vcc
	v_div_scale_f32 v2, s[4:5], v0, v0, 1.0
	v_rcp_f32_e32 v3, v2
	s_nop 0
	v_fma_f32 v138, -v2, v3, 1.0
	v_fmac_f32_e32 v3, v138, v3
	v_div_scale_f32 v138, vcc, 1.0, v0, 1.0
	v_mul_f32_e32 v139, v138, v3
	v_fma_f32 v140, -v2, v139, v138
	v_fmac_f32_e32 v139, v140, v3
	v_fma_f32 v2, -v2, v139, v138
	v_div_fmas_f32 v2, v2, v3, v139
	v_div_fixup_f32 v0, v2, v0, 1.0
	v_pk_mul_f32 v[20:21], v[20:21], v[0:1] op_sel_hi:[1,0]
	v_pk_mul_f32 v[18:19], v[18:19], v[0:1] op_sel_hi:[1,0]
	v_pk_mul_f32 v[16:17], v[16:17], v[0:1] op_sel_hi:[1,0]
	v_pk_mul_f32 v[14:15], v[14:15], v[0:1] op_sel_hi:[1,0]
	v_pk_mul_f32 v[12:13], v[12:13], v[0:1] op_sel_hi:[1,0]
	v_pk_mul_f32 v[10:11], v[10:11], v[0:1] op_sel_hi:[1,0]
	v_pk_mul_f32 v[8:9], v[8:9], v[0:1] op_sel_hi:[1,0]
	v_pk_mul_f32 v[6:7], v[6:7], v[0:1] op_sel_hi:[1,0]
